# p0a weight-transpose loop rebalanced: WGs that also do the modulation item take 2 transposes per wave, the others 7
# baseline (speedup 1.0000x reference)
.LBB0_19:
	s_load_dwordx16 s[36:51], s[0:1], 0x0
	s_load_dwordx16 s[16:31], s[0:1], 0x40
	s_lshr_b32 s71, s12, 6
	s_cmp_lt_i32 s78, 1
	v_and_b32_e32 v233, 63, v232
	s_waitcnt lgkmcnt(0)
	v_writelane_b32 v254, s16, 2
	s_nop 1
	v_writelane_b32 v254, s17, 3
	v_writelane_b32 v254, s18, 4
	v_writelane_b32 v254, s19, 5
	v_writelane_b32 v254, s20, 6
	v_writelane_b32 v254, s21, 7
	v_writelane_b32 v254, s22, 8
	v_writelane_b32 v254, s23, 9
	v_writelane_b32 v254, s24, 10
	v_writelane_b32 v254, s25, 11
	v_writelane_b32 v254, s26, 12
	v_writelane_b32 v254, s27, 13
	v_writelane_b32 v254, s28, 14
	v_writelane_b32 v254, s29, 15
	v_writelane_b32 v254, s30, 16
	v_writelane_b32 v254, s31, 17
	s_cselect_b64 s[22:23], -1, 0
	s_cmp_gt_i32 s79, 0
	s_cselect_b64 s[0:1], -1, 0
	s_and_b64 s[0:1], s[22:23], s[0:1]
	s_andn2_b64 vcc, exec, s[0:1]
	s_cbranch_vccnz .LBB0_109
	s_mov_b32 s54, s3
	v_mov_b32_e32 v2, v233
	s_mov_b32 s55, s2
	v_mov_b32_e32 v0, v232
	s_mov_b32 s16, s71
	s_mov_b64 s[24:25], 0
	s_add_u32 s63, s76, s24
	s_addc_u32 s96, s77, s25
	s_add_u32 s6, s63, 0x100000
	s_addc_u32 s7, s96, 0
	s_lshl_b32 s0, s55, 3
	s_add_i32 s12, s0, s16
	s_cmpk_lt_i32 s12, 0x600
	s_movk_i32 s101, 0x200
	s_movk_i32 s100, 0x19ff
	s_cbranch_scc0 .Lp0a_hi
	s_movk_i32 s101, 0x600
	s_movk_i32 s100, 0xbff
	s_branch .Lp0a_go
.Lp0a_hi:
	s_addk_i32 s12, 0x600
.Lp0a_go:
	s_cmp_gt_i32 s12, s100
	s_cbranch_scc1 .LBB0_53
	s_add_u32 s13, s63, 0x1900000
	s_mul_i32 s0, s16, 0x2100
	v_lshlrev_b32_e32 v3, 2, v2
	s_addc_u32 s14, s96, 0
	s_add_i32 s0, s0, 0
	v_ashrrev_i32_e32 v1, 3, v2
	v_and_b32_e32 v4, 28, v3
	s_movk_i32 s4, 0x84
	v_lshlrev_b32_e32 v6, 3, v2
	v_lshl_add_u32 v7, v4, 2, s0
	v_mul_lo_u32 v11, v1, s4
	v_and_b32_e32 v6, 56, v6
	v_mul_u32_u24_e32 v10, 0x84, v6
	v_lshlrev_b32_e32 v12, 2, v1
	v_add_u32_e32 v11, v7, v11
	s_lshl_b32 s15, s54, 3
	s_mov_b32 s1, 0
	v_mov_b32_e32 v5, 0
	v_add_u32_e32 v3, 8, v1
	v_add_u32_e32 v8, 16, v1
	v_add_u32_e32 v9, 24, v1
	v_add3_u32 v10, s0, v10, v12
	s_mov_b32 s17, 0x8000
	s_mov_b32 s18, 0x10000
	s_mov_b32 s19, 0x18000
	s_mov_b32 s20, 0x20000
	s_mov_b32 s21, 0x28000
	s_mov_b32 s26, 0x30000
	s_mov_b32 s27, 0x38000
	v_add_u32_e32 v12, 0x420, v11
	v_add_u32_e32 v13, 0x428, v11
	v_add_u32_e32 v14, 0x840, v11
	v_add_u32_e32 v15, 0x848, v11
	v_add_u32_e32 v16, 0xc60, v11
	v_add_u32_e32 v17, 0xc68, v11
	v_add_u32_e32 v18, 0x1080, v11
	v_add_u32_e32 v19, 0x1088, v11
	v_add_u32_e32 v20, 0x14a0, v11
	v_add_u32_e32 v21, 0x14a8, v11
	v_add_u32_e32 v22, 0x18c0, v11
	v_add_u32_e32 v23, 0x18c8, v11
	v_add_u32_e32 v24, 0x1ce0, v11
	v_add_u32_e32 v25, 0x1ce8, v11
	s_movk_i32 s28, 0xa00
	s_movk_i32 s29, 0x2c00
	v_lshlrev_b32_e32 v4, 2, v4
	v_lshlrev_b32_e32 v6, 1, v6
	s_branch .LBB0_24

.LBB0_23:
	s_add_i32 s12, s12, s101
	s_cmp_gt_i32 s12, s100
	s_cbranch_scc1 .LBB0_53
